# mlp1: next tile's completion records fetched asynchronously at the start of the current tile's main loop (blocking poll only as fallback)
# speedup vs baseline: 1.0272x; 1.0058x over previous
.LBB0_74:
	s_add_i32 s0, s18, -2
	s_mul_hi_u32 s1, s0, 0xcccccccd
	s_lshr_b32 s1, s1, 2
	s_mul_i32 s5, s1, 5
	s_sub_i32 s5, s0, s5
	s_cmp_lt_i32 s18, 2
	s_cselect_b32 s8, 0, s1
	s_mov_b32 s9, s21
	s_cselect_b32 s6, s0, s5
	s_lshl_b64 s[0:1], s[8:9], 23
	v_writelane_b32 v255, s0, 35
	s_lshl_b32 s5, s8, 10
	s_nop 0
	v_writelane_b32 v255, s1, 36
	s_mul_i32 s0, s8, 3
	v_writelane_b32 v255, s0, 37
	s_mul_i32 s0, s8, 0x60
	v_writelane_b32 v255, s0, 38
	s_nop 1
	v_writelane_b32 v255, s1, 39
	v_writelane_b32 v255, s8, 40
	s_cmp_lt_u32 s8, 3
	s_cselect_b64 s[0:1], -1, 0
	v_writelane_b32 v255, s9, 41
	v_readlane_b32 s8, v254, 37
	v_readlane_b32 s9, v254, 38
	s_and_b64 s[0:1], s[8:9], s[0:1]
	v_writelane_b32 v255, s0, 42
	s_mov_b64 s[8:9], 0
	s_cmp_lt_i32 s6, 1
	v_writelane_b32 v255, s1, 43
	v_writelane_b32 v255, s6, 44
	v_writelane_b32 v255, s8, 45
	s_mov_b64 s[0:1], -1
	s_nop 0
	v_writelane_b32 v255, s9, 46
	s_cbranch_scc1 .LBB0_339
	v_readlane_b32 s0, v255, 44
	s_cmp_gt_i32 s0, 1
	s_cbranch_scc0 .LBB0_87
	s_cmp_gt_i32 s0, 2
	s_cbranch_scc0 .LBB0_88
	s_cmp_eq_u32 s0, 3
	s_mov_b64 s[0:1], -1
	s_cbranch_scc0 .LBB0_90
	s_mov_b64 s[22:23], 0
	s_mov_b64 s[0:1], 0
	v_mov_b32_e32 v0, v137
	v_readlane_b32 s8, v254, 33
	v_readlane_b32 s9, v254, 34
	v_readfirstlane_b32 s0, v0
	s_ashr_i32 s0, s0, 6
	s_andn2_b64 vcc, exec, s[8:9]
	s_cbranch_vccnz .LBB0_89
	s_and_b32 s1, s0, 1
	s_ashr_i32 s6, s0, 1
	s_add_u32 s12, s94, s22
	s_addc_u32 s13, s95, s23
	v_readlane_b32 s16, v255, 35
	v_readlane_b32 s17, v255, 36
	s_add_u32 s8, s12, s16
	s_addc_u32 s9, s13, s17
	s_add_u32 s26, s8, 0x2300000
	s_addc_u32 s27, s9, 0
	s_add_u32 s34, s12, 0x7b48000
	v_bfe_u32 v8, v0, 3, 3
	s_addc_u32 s35, s13, 0
	v_lshl_or_b32 v98, s0, 5, v8
	s_lshl_b32 s8, s0, 12
	s_lshl_b32 s9, s0, 11
	s_lshl_b32 s11, s6, 13
	s_lshl_b32 s6, s6, 6
	s_lshl_b32 s14, s1, 13
	s_lshl_b32 s19, s1, 6
	v_bfe_u32 v3, v0, 4, 2
	v_ashrrev_i32_e32 v99, 31, v98
	v_lshl_or_b32 v104, s0, 4, v8
	s_add_u32 s0, s12, 0xe1d8000
	v_and_b32_e32 v2, 15, v0
	v_lshlrev_b64 v[4:5], 11, v[98:99]
	v_and_b32_e32 v10, 7, v0
	v_bitop3_b32 v9, v8, v0, 7 bitop3:0x78
	v_bitop3_b32 v0, v3, v0, 7 bitop3:0x78
	s_addc_u32 s1, s13, 0
	v_lshl_add_u64 v[6:7], s[34:35], 0, v[4:5]
	v_lshlrev_b32_e32 v100, 4, v9
	v_mov_b32_e32 v101, v1
	v_ashrrev_i32_e32 v105, 31, v104
	v_lshlrev_b32_e32 v120, 4, v0
	v_or_b32_e32 v0, s6, v2
	v_lshl_or_b32 v125, v3, 2, s6
	s_add_u32 s6, s22, s16
	v_lshl_add_u64 v[102:103], v[6:7], 0, v[100:101]
	v_lshlrev_b64 v[6:7], 11, v[104:105]
	v_lshlrev_b32_e32 v99, 7, v2
	v_or_b32_e32 v11, s19, v2
	v_bitop3_b32 v10, v3, v10, 4 bitop3:0x36
	v_lshl_add_u64 v[112:113], s[12:13], 0, v[4:5]
	s_addc_u32 s13, s23, s17
	v_lshl_add_u64 v[8:9], s[26:27], 0, v[6:7]
	v_or_b32_e32 v105, s11, v99
	v_lshlrev_b32_e32 v121, 7, v0
	v_or_b32_e32 v122, s14, v99
	v_lshlrev_b32_e32 v123, 7, v11
	v_lshlrev_b32_e32 v124, 4, v10
	s_add_u32 s12, s94, s6
	v_lshl_add_u64 v[106:107], v[8:9], 0, v[100:101]
	v_or_b32_e32 v0, 0x800, v121
	v_or_b32_e32 v8, 0x1000, v121
	v_or_b32_e32 v9, 0x1800, v121
	v_or_b32_e32 v11, 0x800, v123
	v_or_b32_e32 v12, 0x1000, v123
	v_or_b32_e32 v13, 0x1800, v123
	v_or_b32_e32 v3, 0x18000, v124
	v_or_b32_e32 v10, 0x20000, v122
	s_waitcnt vmcnt(0)
	v_or_b32_e32 v14, 0x20000, v124
	v_add_u32_e32 v15, 0xc000, v105
	v_add_u32_e32 v16, 0xc000, v121
	v_or_b32_e32 v17, 0xc000, v122
	v_or_b32_e32 v18, 0xc000, v123
	s_addc_u32 s13, s95, s13
	v_or_b32_e32 v127, s11, v124
	v_or_b32_e32 v4, s14, v120
	s_add_i32 s11, s11, 0xc000
	v_add_u32_e32 v135, v122, v120
	v_lshl_add_u64 v[108:109], s[34:35], 0, v[100:101]
	v_lshl_add_u64 v[110:111], s[26:27], 0, v[100:101]
	v_add_u32_e32 v126, 0x18000, v105
	v_lshl_add_u64 v[114:115], s[12:13], 0, v[6:7]
	v_or_b32_e32 v128, 0x15000, v4
	v_or_b32_e32 v129, 0x14800, v4
	v_or_b32_e32 v130, 0x14000, v4
	v_or_b32_e32 v131, s14, v124
	v_or_b32_e32 v132, s11, v120
	s_mov_b64 s[38:39], 0
	s_add_i32 s11, s8, 0x400
	s_add_i32 s12, s8, 0xc00
	s_add_i32 s13, s9, 0x8000
	s_add_i32 s40, s9, 0x8400
	s_add_i32 s41, s8, 0xc400
	s_add_i32 s42, s8, 0xc800
	s_add_i32 s43, s8, 0xcc00
	s_add_i32 s44, s9, 0x14400
	s_add_i32 s45, s8, 0x18400
	s_add_i32 s46, s8, 0x18800
	s_add_i32 s47, s8, 0x18c00
	s_add_i32 s48, s9, 0x20400
	v_add_u32_e32 v133, v105, v120
	v_add_u32_e32 v134, v121, v120
	v_add_u32_e32 v161, v123, v120
	v_add_u32_e32 v163, v15, v124
	v_add_u32_e32 v164, v16, v124
	v_add_u32_e32 v165, v17, v124
	v_add_u32_e32 v166, v18, v124
	v_add3_u32 v167, v121, v120, s29
	v_or_b32_e32 v168, 0x20000, v135
	v_add_u32_e32 v169, v3, v0
	v_add_u32_e32 v170, v3, v8
	v_add_u32_e32 v171, v3, v9
	v_add_u32_e32 v172, v10, v124
	v_add_u32_e32 v173, v14, v11
	v_add_u32_e32 v174, v14, v12
	v_add_u32_e32 v175, v14, v13
	s_lshl_b32 s20, s19, 1
	v_lshlrev_b32_e32 v0, 1, v2
	v_readlane_b32 s49, v253, 0
	s_mov_b32 s66, 0
	s_load_dword s67, s[78:79], 0x0
	s_waitcnt lgkmcnt(0)
	s_branch .LBB0_81
.LBB0_80:
	s_lshl_b32 s66, s26, 1
	s_lshr_b32 s53, s22, 3
	s_add_i32 s66, s66, s53
	s_add_i32 s66, s66, 1
	v_readfirstlane_b32 s6, v137
	s_lshr_b32 s6, s6, 6
	s_and_b32 s14, s6, 1
	s_lshr_b32 s19, s6, 1
	s_lshl_b32 s19, s19, 6
	s_add_i32 s19, s19, s26
	s_lshl_b32 s14, s14, 6
	s_add_i32 s14, s14, s22
	s_lshl_b32 s6, s6, 12
	s_add_i32 s6, s6, 0x18000
	v_and_b32_e32 v202, 63, v137
	v_and_b32_e32 v203, 15, v202
	v_lshrrev_b32_e32 v204, 4, v202
	v_and_b32_e32 v205, 3, v203
	v_lshrrev_b32_e32 v206, 2, v203
	v_lshl_or_b32 v207, v204, 2, v205
	s_mov_b32 s36, 0xaaaaaaaa
	s_mov_b32 s37, 0xaaaaaaaa
	s_mov_b32 s50, 0xcccccccc
	s_mov_b32 s51, 0xcccccccc
	v_and_b32_e32 v208, 7, v207
	v_lshlrev_b32_e32 v208, 1, v208
	v_or_b32_e32 v209, 0, v206
	v_xor_b32_e32 v209, v209, v208
	v_lshlrev_b32_e32 v209, 3, v209
	v_lshl_add_u32 v209, v207, 7, v209
	v_add_u32_e32 v209, s6, v209
	v_or_b32_e32 v210, 4, v206
	v_xor_b32_e32 v210, v210, v208
	v_lshlrev_b32_e32 v210, 3, v210
	v_lshl_add_u32 v210, v207, 7, v210
	v_add_u32_e32 v210, s6, v210
	v_or_b32_e32 v211, 8, v206
	v_xor_b32_e32 v211, v211, v208
	v_lshlrev_b32_e32 v211, 3, v211
	v_lshl_add_u32 v211, v207, 7, v211
	v_add_u32_e32 v211, s6, v211
	v_or_b32_e32 v212, 12, v206
	v_xor_b32_e32 v212, v212, v208
	v_lshlrev_b32_e32 v212, 3, v212
	v_lshl_add_u32 v212, v207, 7, v212
	v_add_u32_e32 v212, s6, v212
	v_lshl_add_u32 v213, v202, 4, s6
	v_lshrrev_b32_e32 v214, 3, v202
	v_and_b32_e32 v215, 7, v202
	v_xor_b32_e32 v215, v215, v214
	v_add_u32_e32 v214, s19, v214
	v_lshlrev_b32_e32 v214, 13, v214
	v_lshl_add_u32 v214, v215, 4, v214
	s_lshl_b32 s27, s14, 1
	v_add_u32_e32 v214, s27, v214
	s_add_u32 s16, s94, 0xe1d8000
	s_addc_u32 s17, s95, 0
	v_max_f32_e32 v62, 0, v62
	v_max_f32_e32 v63, 0, v63
	v_max_f32_e32 v64, 0, v64
	v_max_f32_e32 v65, 0, v65
	v_mul_f32_e32 v62, v62, v62
	v_mul_f32_e32 v63, v63, v63
	v_mul_f32_e32 v64, v64, v64
	v_mul_f32_e32 v65, v65, v65
	v_max_f32_e32 v58, 0, v58
	v_max_f32_e32 v59, 0, v59
	v_max_f32_e32 v60, 0, v60
	v_max_f32_e32 v61, 0, v61
	v_mul_f32_e32 v58, v58, v58
	v_mul_f32_e32 v59, v59, v59
	v_mul_f32_e32 v60, v60, v60
	v_mul_f32_e32 v61, v61, v61
	v_max_f32_e32 v54, 0, v54
	v_max_f32_e32 v55, 0, v55
	v_max_f32_e32 v56, 0, v56
	v_max_f32_e32 v57, 0, v57
	v_mul_f32_e32 v54, v54, v54
	v_mul_f32_e32 v55, v55, v55
	v_mul_f32_e32 v56, v56, v56
	v_mul_f32_e32 v57, v57, v57
	v_max_f32_e32 v50, 0, v50
	v_max_f32_e32 v51, 0, v51
	v_max_f32_e32 v52, 0, v52
	v_max_f32_e32 v53, 0, v53
	v_mul_f32_e32 v50, v50, v50
	v_mul_f32_e32 v51, v51, v51
	v_mul_f32_e32 v52, v52, v52
	v_mul_f32_e32 v53, v53, v53
	v_max_f32_e32 v46, 0, v46
	v_max_f32_e32 v47, 0, v47
	v_max_f32_e32 v48, 0, v48
	v_max_f32_e32 v49, 0, v49
	v_mul_f32_e32 v46, v46, v46
	v_mul_f32_e32 v47, v47, v47
	v_mul_f32_e32 v48, v48, v48
	v_mul_f32_e32 v49, v49, v49
	v_max_f32_e32 v42, 0, v42
	v_max_f32_e32 v43, 0, v43
	v_max_f32_e32 v44, 0, v44
	v_max_f32_e32 v45, 0, v45
	v_mul_f32_e32 v42, v42, v42
	v_mul_f32_e32 v43, v43, v43
	v_mul_f32_e32 v44, v44, v44
	v_mul_f32_e32 v45, v45, v45
	v_max_f32_e32 v38, 0, v38
	v_max_f32_e32 v39, 0, v39
	v_max_f32_e32 v40, 0, v40
	v_max_f32_e32 v41, 0, v41
	v_mul_f32_e32 v38, v38, v38
	v_mul_f32_e32 v39, v39, v39
	v_mul_f32_e32 v40, v40, v40
	v_mul_f32_e32 v41, v41, v41
	v_max_f32_e32 v34, 0, v34
	v_max_f32_e32 v35, 0, v35
	v_max_f32_e32 v36, 0, v36
	v_max_f32_e32 v37, 0, v37
	v_mul_f32_e32 v34, v34, v34
	v_mul_f32_e32 v35, v35, v35
	v_mul_f32_e32 v36, v36, v36
	v_mul_f32_e32 v37, v37, v37
	s_nop 1
	v_mov_b32_dpp v72, v63 quad_perm:[1,0,3,2] row_mask:0xf bank_mask:0xf
	v_mov_b32_dpp v73, v62 quad_perm:[1,0,3,2] row_mask:0xf bank_mask:0xf
	v_mov_b32_dpp v74, v65 quad_perm:[1,0,3,2] row_mask:0xf bank_mask:0xf
	v_mov_b32_dpp v75, v64 quad_perm:[1,0,3,2] row_mask:0xf bank_mask:0xf
	v_cndmask_b32_e64 v62, v62, v72, s[36:37]
	v_cndmask_b32_e64 v63, v73, v63, s[36:37]
	v_cndmask_b32_e64 v64, v64, v74, s[36:37]
	v_cndmask_b32_e64 v65, v75, v65, s[36:37]
	s_nop 1
	v_mov_b32_dpp v74, v62 quad_perm:[2,3,0,1] row_mask:0xf bank_mask:0xf
	v_mov_b32_dpp v75, v63 quad_perm:[2,3,0,1] row_mask:0xf bank_mask:0xf
	v_mov_b32_dpp v72, v64 quad_perm:[2,3,0,1] row_mask:0xf bank_mask:0xf
	v_mov_b32_dpp v73, v65 quad_perm:[2,3,0,1] row_mask:0xf bank_mask:0xf
	v_cndmask_b32_e64 v62, v62, v72, s[50:51]
	v_cndmask_b32_e64 v63, v63, v73, s[50:51]
	v_cndmask_b32_e64 v64, v74, v64, s[50:51]
	v_cndmask_b32_e64 v65, v75, v65, s[50:51]
	s_nop 1
	v_mov_b32_dpp v72, v59 quad_perm:[1,0,3,2] row_mask:0xf bank_mask:0xf
	v_mov_b32_dpp v73, v58 quad_perm:[1,0,3,2] row_mask:0xf bank_mask:0xf
	v_mov_b32_dpp v74, v61 quad_perm:[1,0,3,2] row_mask:0xf bank_mask:0xf
	v_mov_b32_dpp v75, v60 quad_perm:[1,0,3,2] row_mask:0xf bank_mask:0xf
	v_cndmask_b32_e64 v58, v58, v72, s[36:37]
	v_cndmask_b32_e64 v59, v73, v59, s[36:37]
	v_cndmask_b32_e64 v60, v60, v74, s[36:37]
	v_cndmask_b32_e64 v61, v75, v61, s[36:37]
	s_nop 1
	v_mov_b32_dpp v74, v58 quad_perm:[2,3,0,1] row_mask:0xf bank_mask:0xf
	v_mov_b32_dpp v75, v59 quad_perm:[2,3,0,1] row_mask:0xf bank_mask:0xf
	v_mov_b32_dpp v72, v60 quad_perm:[2,3,0,1] row_mask:0xf bank_mask:0xf
	v_mov_b32_dpp v73, v61 quad_perm:[2,3,0,1] row_mask:0xf bank_mask:0xf
	v_cndmask_b32_e64 v58, v58, v72, s[50:51]
	v_cndmask_b32_e64 v59, v59, v73, s[50:51]
	v_cndmask_b32_e64 v60, v74, v60, s[50:51]
	v_cndmask_b32_e64 v61, v75, v61, s[50:51]
	s_nop 1
	v_mov_b32_dpp v72, v55 quad_perm:[1,0,3,2] row_mask:0xf bank_mask:0xf
	v_mov_b32_dpp v73, v54 quad_perm:[1,0,3,2] row_mask:0xf bank_mask:0xf
	v_mov_b32_dpp v74, v57 quad_perm:[1,0,3,2] row_mask:0xf bank_mask:0xf
	v_mov_b32_dpp v75, v56 quad_perm:[1,0,3,2] row_mask:0xf bank_mask:0xf
	v_cndmask_b32_e64 v54, v54, v72, s[36:37]
	v_cndmask_b32_e64 v55, v73, v55, s[36:37]
	v_cndmask_b32_e64 v56, v56, v74, s[36:37]
	v_cndmask_b32_e64 v57, v75, v57, s[36:37]
	s_nop 1
	v_mov_b32_dpp v74, v54 quad_perm:[2,3,0,1] row_mask:0xf bank_mask:0xf
	v_mov_b32_dpp v75, v55 quad_perm:[2,3,0,1] row_mask:0xf bank_mask:0xf
	v_mov_b32_dpp v72, v56 quad_perm:[2,3,0,1] row_mask:0xf bank_mask:0xf
	v_mov_b32_dpp v73, v57 quad_perm:[2,3,0,1] row_mask:0xf bank_mask:0xf
	v_cndmask_b32_e64 v54, v54, v72, s[50:51]
	v_cndmask_b32_e64 v55, v55, v73, s[50:51]
	v_cndmask_b32_e64 v56, v74, v56, s[50:51]
	v_cndmask_b32_e64 v57, v75, v57, s[50:51]
	s_nop 1
	v_mov_b32_dpp v72, v51 quad_perm:[1,0,3,2] row_mask:0xf bank_mask:0xf
	v_mov_b32_dpp v73, v50 quad_perm:[1,0,3,2] row_mask:0xf bank_mask:0xf
	v_mov_b32_dpp v74, v53 quad_perm:[1,0,3,2] row_mask:0xf bank_mask:0xf
	v_mov_b32_dpp v75, v52 quad_perm:[1,0,3,2] row_mask:0xf bank_mask:0xf
	v_cndmask_b32_e64 v50, v50, v72, s[36:37]
	v_cndmask_b32_e64 v51, v73, v51, s[36:37]
	v_cndmask_b32_e64 v52, v52, v74, s[36:37]
	v_cndmask_b32_e64 v53, v75, v53, s[36:37]
	s_nop 1
	v_mov_b32_dpp v74, v50 quad_perm:[2,3,0,1] row_mask:0xf bank_mask:0xf
	v_mov_b32_dpp v75, v51 quad_perm:[2,3,0,1] row_mask:0xf bank_mask:0xf
	v_mov_b32_dpp v72, v52 quad_perm:[2,3,0,1] row_mask:0xf bank_mask:0xf
	v_mov_b32_dpp v73, v53 quad_perm:[2,3,0,1] row_mask:0xf bank_mask:0xf
	v_cndmask_b32_e64 v50, v50, v72, s[50:51]
	v_cndmask_b32_e64 v51, v51, v73, s[50:51]
	v_cndmask_b32_e64 v52, v74, v52, s[50:51]
	v_cndmask_b32_e64 v53, v75, v53, s[50:51]
	s_nop 1
	v_mov_b32_dpp v72, v47 quad_perm:[1,0,3,2] row_mask:0xf bank_mask:0xf
	v_mov_b32_dpp v73, v46 quad_perm:[1,0,3,2] row_mask:0xf bank_mask:0xf
	v_mov_b32_dpp v74, v49 quad_perm:[1,0,3,2] row_mask:0xf bank_mask:0xf
	v_mov_b32_dpp v75, v48 quad_perm:[1,0,3,2] row_mask:0xf bank_mask:0xf
	v_cndmask_b32_e64 v46, v46, v72, s[36:37]
	v_cndmask_b32_e64 v47, v73, v47, s[36:37]
	v_cndmask_b32_e64 v48, v48, v74, s[36:37]
	v_cndmask_b32_e64 v49, v75, v49, s[36:37]
	s_nop 1
	v_mov_b32_dpp v74, v46 quad_perm:[2,3,0,1] row_mask:0xf bank_mask:0xf
	v_mov_b32_dpp v75, v47 quad_perm:[2,3,0,1] row_mask:0xf bank_mask:0xf
	v_mov_b32_dpp v72, v48 quad_perm:[2,3,0,1] row_mask:0xf bank_mask:0xf
	v_mov_b32_dpp v73, v49 quad_perm:[2,3,0,1] row_mask:0xf bank_mask:0xf
	v_cndmask_b32_e64 v46, v46, v72, s[50:51]
	v_cndmask_b32_e64 v47, v47, v73, s[50:51]
	v_cndmask_b32_e64 v48, v74, v48, s[50:51]
	v_cndmask_b32_e64 v49, v75, v49, s[50:51]
	s_nop 1
	v_mov_b32_dpp v72, v43 quad_perm:[1,0,3,2] row_mask:0xf bank_mask:0xf
	v_mov_b32_dpp v73, v42 quad_perm:[1,0,3,2] row_mask:0xf bank_mask:0xf
	v_mov_b32_dpp v74, v45 quad_perm:[1,0,3,2] row_mask:0xf bank_mask:0xf
	v_mov_b32_dpp v75, v44 quad_perm:[1,0,3,2] row_mask:0xf bank_mask:0xf
	v_cndmask_b32_e64 v42, v42, v72, s[36:37]
	v_cndmask_b32_e64 v43, v73, v43, s[36:37]
	v_cndmask_b32_e64 v44, v44, v74, s[36:37]
	v_cndmask_b32_e64 v45, v75, v45, s[36:37]
	s_nop 1
	v_mov_b32_dpp v74, v42 quad_perm:[2,3,0,1] row_mask:0xf bank_mask:0xf
	v_mov_b32_dpp v75, v43 quad_perm:[2,3,0,1] row_mask:0xf bank_mask:0xf
	v_mov_b32_dpp v72, v44 quad_perm:[2,3,0,1] row_mask:0xf bank_mask:0xf
	v_mov_b32_dpp v73, v45 quad_perm:[2,3,0,1] row_mask:0xf bank_mask:0xf
	v_cndmask_b32_e64 v42, v42, v72, s[50:51]
	v_cndmask_b32_e64 v43, v43, v73, s[50:51]
	v_cndmask_b32_e64 v44, v74, v44, s[50:51]
	v_cndmask_b32_e64 v45, v75, v45, s[50:51]
	s_nop 1
	v_mov_b32_dpp v72, v39 quad_perm:[1,0,3,2] row_mask:0xf bank_mask:0xf
	v_mov_b32_dpp v73, v38 quad_perm:[1,0,3,2] row_mask:0xf bank_mask:0xf
	v_mov_b32_dpp v74, v41 quad_perm:[1,0,3,2] row_mask:0xf bank_mask:0xf
	v_mov_b32_dpp v75, v40 quad_perm:[1,0,3,2] row_mask:0xf bank_mask:0xf
	v_cndmask_b32_e64 v38, v38, v72, s[36:37]
	v_cndmask_b32_e64 v39, v73, v39, s[36:37]
	v_cndmask_b32_e64 v40, v40, v74, s[36:37]
	v_cndmask_b32_e64 v41, v75, v41, s[36:37]
	s_nop 1
	v_mov_b32_dpp v74, v38 quad_perm:[2,3,0,1] row_mask:0xf bank_mask:0xf
	v_mov_b32_dpp v75, v39 quad_perm:[2,3,0,1] row_mask:0xf bank_mask:0xf
	v_mov_b32_dpp v72, v40 quad_perm:[2,3,0,1] row_mask:0xf bank_mask:0xf
	v_mov_b32_dpp v73, v41 quad_perm:[2,3,0,1] row_mask:0xf bank_mask:0xf
	v_cndmask_b32_e64 v38, v38, v72, s[50:51]
	v_cndmask_b32_e64 v39, v39, v73, s[50:51]
	v_cndmask_b32_e64 v40, v74, v40, s[50:51]
	v_cndmask_b32_e64 v41, v75, v41, s[50:51]
	s_nop 1
	v_mov_b32_dpp v72, v35 quad_perm:[1,0,3,2] row_mask:0xf bank_mask:0xf
	v_mov_b32_dpp v73, v34 quad_perm:[1,0,3,2] row_mask:0xf bank_mask:0xf
	v_mov_b32_dpp v74, v37 quad_perm:[1,0,3,2] row_mask:0xf bank_mask:0xf
	v_mov_b32_dpp v75, v36 quad_perm:[1,0,3,2] row_mask:0xf bank_mask:0xf
	v_cndmask_b32_e64 v34, v34, v72, s[36:37]
	v_cndmask_b32_e64 v35, v73, v35, s[36:37]
	v_cndmask_b32_e64 v36, v36, v74, s[36:37]
	v_cndmask_b32_e64 v37, v75, v37, s[36:37]
	s_nop 1
	v_mov_b32_dpp v74, v34 quad_perm:[2,3,0,1] row_mask:0xf bank_mask:0xf
	v_mov_b32_dpp v75, v35 quad_perm:[2,3,0,1] row_mask:0xf bank_mask:0xf
	v_mov_b32_dpp v72, v36 quad_perm:[2,3,0,1] row_mask:0xf bank_mask:0xf
	v_mov_b32_dpp v73, v37 quad_perm:[2,3,0,1] row_mask:0xf bank_mask:0xf
	v_cndmask_b32_e64 v34, v34, v72, s[50:51]
	v_cndmask_b32_e64 v35, v35, v73, s[50:51]
	v_cndmask_b32_e64 v36, v74, v36, s[50:51]
	v_cndmask_b32_e64 v37, v75, v37, s[50:51]
	v_cvt_pk_bf16_f32 v62, v62, v63
	v_cvt_pk_bf16_f32 v63, v64, v65
	ds_write_b64 v209, v[62:63] offset:0
	v_cvt_pk_bf16_f32 v58, v58, v59
	v_cvt_pk_bf16_f32 v59, v60, v61
	ds_write_b64 v210, v[58:59] offset:0
	v_cvt_pk_bf16_f32 v54, v54, v55
	v_cvt_pk_bf16_f32 v55, v56, v57
	ds_write_b64 v211, v[54:55] offset:0
	v_cvt_pk_bf16_f32 v50, v50, v51
	v_cvt_pk_bf16_f32 v51, v52, v53
	ds_write_b64 v212, v[50:51] offset:0
	v_cvt_pk_bf16_f32 v46, v46, v47
	v_cvt_pk_bf16_f32 v47, v48, v49
	ds_write_b64 v209, v[46:47] offset:2048
	v_cvt_pk_bf16_f32 v42, v42, v43
	v_cvt_pk_bf16_f32 v43, v44, v45
	ds_write_b64 v210, v[42:43] offset:2048
	v_cvt_pk_bf16_f32 v38, v38, v39
	v_cvt_pk_bf16_f32 v39, v40, v41
	ds_write_b64 v211, v[38:39] offset:2048
	v_cvt_pk_bf16_f32 v34, v34, v35
	v_cvt_pk_bf16_f32 v35, v36, v37
	ds_write_b64 v212, v[34:35] offset:2048
	s_waitcnt lgkmcnt(0)
	ds_read_b128 v[76:79], v213 offset:0
	ds_read_b128 v[80:83], v213 offset:1024
	ds_read_b128 v[84:87], v213 offset:2048
	ds_read_b128 v[88:91], v213 offset:3072
	s_waitcnt lgkmcnt(3)
	global_store_dwordx4 v214, v[76:79], s[16:17] sc1
	s_waitcnt lgkmcnt(2)
	v_add_u32_e32 v216, 0x10000, v214
	global_store_dwordx4 v216, v[80:83], s[16:17] sc1
	s_waitcnt lgkmcnt(1)
	v_add_u32_e32 v216, 0x20000, v214
	global_store_dwordx4 v216, v[84:87], s[16:17] sc1
	s_waitcnt lgkmcnt(0)
	v_add_u32_e32 v216, 0x30000, v214
	global_store_dwordx4 v216, v[88:91], s[16:17] sc1
	s_nop 1
	v_max_f32_e32 v30, 0, v30
	v_max_f32_e32 v31, 0, v31
	v_max_f32_e32 v32, 0, v32
	v_max_f32_e32 v33, 0, v33
	v_mul_f32_e32 v30, v30, v30
	v_mul_f32_e32 v31, v31, v31
	v_mul_f32_e32 v32, v32, v32
	v_mul_f32_e32 v33, v33, v33
	v_max_f32_e32 v26, 0, v26
	v_max_f32_e32 v27, 0, v27
	v_max_f32_e32 v28, 0, v28
	v_max_f32_e32 v29, 0, v29
	v_mul_f32_e32 v26, v26, v26
	v_mul_f32_e32 v27, v27, v27
	v_mul_f32_e32 v28, v28, v28
	v_mul_f32_e32 v29, v29, v29
	v_max_f32_e32 v22, 0, v22
	v_max_f32_e32 v23, 0, v23
	v_max_f32_e32 v24, 0, v24
	v_max_f32_e32 v25, 0, v25
	v_mul_f32_e32 v22, v22, v22
	v_mul_f32_e32 v23, v23, v23
	v_mul_f32_e32 v24, v24, v24
	v_mul_f32_e32 v25, v25, v25
	v_max_f32_e32 v18, 0, v18
	v_max_f32_e32 v19, 0, v19
	v_max_f32_e32 v20, 0, v20
	v_max_f32_e32 v21, 0, v21
	v_mul_f32_e32 v18, v18, v18
	v_mul_f32_e32 v19, v19, v19
	v_mul_f32_e32 v20, v20, v20
	v_mul_f32_e32 v21, v21, v21
	v_max_f32_e32 v14, 0, v14
	v_max_f32_e32 v15, 0, v15
	v_max_f32_e32 v16, 0, v16
	v_max_f32_e32 v17, 0, v17
	v_mul_f32_e32 v14, v14, v14
	v_mul_f32_e32 v15, v15, v15
	v_mul_f32_e32 v16, v16, v16
	v_mul_f32_e32 v17, v17, v17
	v_max_f32_e32 v10, 0, v10
	v_max_f32_e32 v11, 0, v11
	v_max_f32_e32 v12, 0, v12
	v_max_f32_e32 v13, 0, v13
	v_mul_f32_e32 v10, v10, v10
	v_mul_f32_e32 v11, v11, v11
	v_mul_f32_e32 v12, v12, v12
	v_mul_f32_e32 v13, v13, v13
	v_max_f32_e32 v6, 0, v6
	v_max_f32_e32 v7, 0, v7
	v_max_f32_e32 v8, 0, v8
	v_max_f32_e32 v9, 0, v9
	v_mul_f32_e32 v6, v6, v6
	v_mul_f32_e32 v7, v7, v7
	v_mul_f32_e32 v8, v8, v8
	v_mul_f32_e32 v9, v9, v9
	v_max_f32_e32 v2, 0, v2
	v_max_f32_e32 v3, 0, v3
	v_max_f32_e32 v4, 0, v4
	v_max_f32_e32 v5, 0, v5
	v_mul_f32_e32 v2, v2, v2
	v_mul_f32_e32 v3, v3, v3
	v_mul_f32_e32 v4, v4, v4
	v_mul_f32_e32 v5, v5, v5
	s_nop 1
	v_mov_b32_dpp v72, v31 quad_perm:[1,0,3,2] row_mask:0xf bank_mask:0xf
	v_mov_b32_dpp v73, v30 quad_perm:[1,0,3,2] row_mask:0xf bank_mask:0xf
	v_mov_b32_dpp v74, v33 quad_perm:[1,0,3,2] row_mask:0xf bank_mask:0xf
	v_mov_b32_dpp v75, v32 quad_perm:[1,0,3,2] row_mask:0xf bank_mask:0xf
	v_cndmask_b32_e64 v30, v30, v72, s[36:37]
	v_cndmask_b32_e64 v31, v73, v31, s[36:37]
	v_cndmask_b32_e64 v32, v32, v74, s[36:37]
	v_cndmask_b32_e64 v33, v75, v33, s[36:37]
	s_nop 1
	v_mov_b32_dpp v74, v30 quad_perm:[2,3,0,1] row_mask:0xf bank_mask:0xf
	v_mov_b32_dpp v75, v31 quad_perm:[2,3,0,1] row_mask:0xf bank_mask:0xf
	v_mov_b32_dpp v72, v32 quad_perm:[2,3,0,1] row_mask:0xf bank_mask:0xf
	v_mov_b32_dpp v73, v33 quad_perm:[2,3,0,1] row_mask:0xf bank_mask:0xf
	v_cndmask_b32_e64 v30, v30, v72, s[50:51]
	v_cndmask_b32_e64 v31, v31, v73, s[50:51]
	v_cndmask_b32_e64 v32, v74, v32, s[50:51]
	v_cndmask_b32_e64 v33, v75, v33, s[50:51]
	s_nop 1
	v_mov_b32_dpp v72, v27 quad_perm:[1,0,3,2] row_mask:0xf bank_mask:0xf
	v_mov_b32_dpp v73, v26 quad_perm:[1,0,3,2] row_mask:0xf bank_mask:0xf
	v_mov_b32_dpp v74, v29 quad_perm:[1,0,3,2] row_mask:0xf bank_mask:0xf
	v_mov_b32_dpp v75, v28 quad_perm:[1,0,3,2] row_mask:0xf bank_mask:0xf
	v_cndmask_b32_e64 v26, v26, v72, s[36:37]
	v_cndmask_b32_e64 v27, v73, v27, s[36:37]
	v_cndmask_b32_e64 v28, v28, v74, s[36:37]
	v_cndmask_b32_e64 v29, v75, v29, s[36:37]
	s_nop 1
	v_mov_b32_dpp v74, v26 quad_perm:[2,3,0,1] row_mask:0xf bank_mask:0xf
	v_mov_b32_dpp v75, v27 quad_perm:[2,3,0,1] row_mask:0xf bank_mask:0xf
	v_mov_b32_dpp v72, v28 quad_perm:[2,3,0,1] row_mask:0xf bank_mask:0xf
	v_mov_b32_dpp v73, v29 quad_perm:[2,3,0,1] row_mask:0xf bank_mask:0xf
	v_cndmask_b32_e64 v26, v26, v72, s[50:51]
	v_cndmask_b32_e64 v27, v27, v73, s[50:51]
	v_cndmask_b32_e64 v28, v74, v28, s[50:51]
	v_cndmask_b32_e64 v29, v75, v29, s[50:51]
	s_nop 1
	v_mov_b32_dpp v72, v23 quad_perm:[1,0,3,2] row_mask:0xf bank_mask:0xf
	v_mov_b32_dpp v73, v22 quad_perm:[1,0,3,2] row_mask:0xf bank_mask:0xf
	v_mov_b32_dpp v74, v25 quad_perm:[1,0,3,2] row_mask:0xf bank_mask:0xf
	v_mov_b32_dpp v75, v24 quad_perm:[1,0,3,2] row_mask:0xf bank_mask:0xf
	v_cndmask_b32_e64 v22, v22, v72, s[36:37]
	v_cndmask_b32_e64 v23, v73, v23, s[36:37]
	v_cndmask_b32_e64 v24, v24, v74, s[36:37]
	v_cndmask_b32_e64 v25, v75, v25, s[36:37]
	s_nop 1
	v_mov_b32_dpp v74, v22 quad_perm:[2,3,0,1] row_mask:0xf bank_mask:0xf
	v_mov_b32_dpp v75, v23 quad_perm:[2,3,0,1] row_mask:0xf bank_mask:0xf
	v_mov_b32_dpp v72, v24 quad_perm:[2,3,0,1] row_mask:0xf bank_mask:0xf
	v_mov_b32_dpp v73, v25 quad_perm:[2,3,0,1] row_mask:0xf bank_mask:0xf
	v_cndmask_b32_e64 v22, v22, v72, s[50:51]
	v_cndmask_b32_e64 v23, v23, v73, s[50:51]
	v_cndmask_b32_e64 v24, v74, v24, s[50:51]
	v_cndmask_b32_e64 v25, v75, v25, s[50:51]
	s_nop 1
	v_mov_b32_dpp v72, v19 quad_perm:[1,0,3,2] row_mask:0xf bank_mask:0xf
	v_mov_b32_dpp v73, v18 quad_perm:[1,0,3,2] row_mask:0xf bank_mask:0xf
	v_mov_b32_dpp v74, v21 quad_perm:[1,0,3,2] row_mask:0xf bank_mask:0xf
	v_mov_b32_dpp v75, v20 quad_perm:[1,0,3,2] row_mask:0xf bank_mask:0xf
	v_cndmask_b32_e64 v18, v18, v72, s[36:37]
	v_cndmask_b32_e64 v19, v73, v19, s[36:37]
	v_cndmask_b32_e64 v20, v20, v74, s[36:37]
	v_cndmask_b32_e64 v21, v75, v21, s[36:37]
	s_nop 1
	v_mov_b32_dpp v74, v18 quad_perm:[2,3,0,1] row_mask:0xf bank_mask:0xf
	v_mov_b32_dpp v75, v19 quad_perm:[2,3,0,1] row_mask:0xf bank_mask:0xf
	v_mov_b32_dpp v72, v20 quad_perm:[2,3,0,1] row_mask:0xf bank_mask:0xf
	v_mov_b32_dpp v73, v21 quad_perm:[2,3,0,1] row_mask:0xf bank_mask:0xf
	v_cndmask_b32_e64 v18, v18, v72, s[50:51]
	v_cndmask_b32_e64 v19, v19, v73, s[50:51]
	v_cndmask_b32_e64 v20, v74, v20, s[50:51]
	v_cndmask_b32_e64 v21, v75, v21, s[50:51]
	s_nop 1
	v_mov_b32_dpp v72, v15 quad_perm:[1,0,3,2] row_mask:0xf bank_mask:0xf
	v_mov_b32_dpp v73, v14 quad_perm:[1,0,3,2] row_mask:0xf bank_mask:0xf
	v_mov_b32_dpp v74, v17 quad_perm:[1,0,3,2] row_mask:0xf bank_mask:0xf
	v_mov_b32_dpp v75, v16 quad_perm:[1,0,3,2] row_mask:0xf bank_mask:0xf
	v_cndmask_b32_e64 v14, v14, v72, s[36:37]
	v_cndmask_b32_e64 v15, v73, v15, s[36:37]
	v_cndmask_b32_e64 v16, v16, v74, s[36:37]
	v_cndmask_b32_e64 v17, v75, v17, s[36:37]
	s_nop 1
	v_mov_b32_dpp v74, v14 quad_perm:[2,3,0,1] row_mask:0xf bank_mask:0xf
	v_mov_b32_dpp v75, v15 quad_perm:[2,3,0,1] row_mask:0xf bank_mask:0xf
	v_mov_b32_dpp v72, v16 quad_perm:[2,3,0,1] row_mask:0xf bank_mask:0xf
	v_mov_b32_dpp v73, v17 quad_perm:[2,3,0,1] row_mask:0xf bank_mask:0xf
	v_cndmask_b32_e64 v14, v14, v72, s[50:51]
	v_cndmask_b32_e64 v15, v15, v73, s[50:51]
	v_cndmask_b32_e64 v16, v74, v16, s[50:51]
	v_cndmask_b32_e64 v17, v75, v17, s[50:51]
	s_nop 1
	v_mov_b32_dpp v72, v11 quad_perm:[1,0,3,2] row_mask:0xf bank_mask:0xf
	v_mov_b32_dpp v73, v10 quad_perm:[1,0,3,2] row_mask:0xf bank_mask:0xf
	v_mov_b32_dpp v74, v13 quad_perm:[1,0,3,2] row_mask:0xf bank_mask:0xf
	v_mov_b32_dpp v75, v12 quad_perm:[1,0,3,2] row_mask:0xf bank_mask:0xf
	v_cndmask_b32_e64 v10, v10, v72, s[36:37]
	v_cndmask_b32_e64 v11, v73, v11, s[36:37]
	v_cndmask_b32_e64 v12, v12, v74, s[36:37]
	v_cndmask_b32_e64 v13, v75, v13, s[36:37]
	s_nop 1
	v_mov_b32_dpp v74, v10 quad_perm:[2,3,0,1] row_mask:0xf bank_mask:0xf
	v_mov_b32_dpp v75, v11 quad_perm:[2,3,0,1] row_mask:0xf bank_mask:0xf
	v_mov_b32_dpp v72, v12 quad_perm:[2,3,0,1] row_mask:0xf bank_mask:0xf
	v_mov_b32_dpp v73, v13 quad_perm:[2,3,0,1] row_mask:0xf bank_mask:0xf
	v_cndmask_b32_e64 v10, v10, v72, s[50:51]
	v_cndmask_b32_e64 v11, v11, v73, s[50:51]
	v_cndmask_b32_e64 v12, v74, v12, s[50:51]
	v_cndmask_b32_e64 v13, v75, v13, s[50:51]
	s_nop 1
	v_mov_b32_dpp v72, v7 quad_perm:[1,0,3,2] row_mask:0xf bank_mask:0xf
	v_mov_b32_dpp v73, v6 quad_perm:[1,0,3,2] row_mask:0xf bank_mask:0xf
	v_mov_b32_dpp v74, v9 quad_perm:[1,0,3,2] row_mask:0xf bank_mask:0xf
	v_mov_b32_dpp v75, v8 quad_perm:[1,0,3,2] row_mask:0xf bank_mask:0xf
	v_cndmask_b32_e64 v6, v6, v72, s[36:37]
	v_cndmask_b32_e64 v7, v73, v7, s[36:37]
	v_cndmask_b32_e64 v8, v8, v74, s[36:37]
	v_cndmask_b32_e64 v9, v75, v9, s[36:37]
	s_nop 1
	v_mov_b32_dpp v74, v6 quad_perm:[2,3,0,1] row_mask:0xf bank_mask:0xf
	v_mov_b32_dpp v75, v7 quad_perm:[2,3,0,1] row_mask:0xf bank_mask:0xf
	v_mov_b32_dpp v72, v8 quad_perm:[2,3,0,1] row_mask:0xf bank_mask:0xf
	v_mov_b32_dpp v73, v9 quad_perm:[2,3,0,1] row_mask:0xf bank_mask:0xf
	v_cndmask_b32_e64 v6, v6, v72, s[50:51]
	v_cndmask_b32_e64 v7, v7, v73, s[50:51]
	v_cndmask_b32_e64 v8, v74, v8, s[50:51]
	v_cndmask_b32_e64 v9, v75, v9, s[50:51]
	s_nop 1
	v_mov_b32_dpp v72, v3 quad_perm:[1,0,3,2] row_mask:0xf bank_mask:0xf
	v_mov_b32_dpp v73, v2 quad_perm:[1,0,3,2] row_mask:0xf bank_mask:0xf
	v_mov_b32_dpp v74, v5 quad_perm:[1,0,3,2] row_mask:0xf bank_mask:0xf
	v_mov_b32_dpp v75, v4 quad_perm:[1,0,3,2] row_mask:0xf bank_mask:0xf
	v_cndmask_b32_e64 v2, v2, v72, s[36:37]
	v_cndmask_b32_e64 v3, v73, v3, s[36:37]
	v_cndmask_b32_e64 v4, v4, v74, s[36:37]
	v_cndmask_b32_e64 v5, v75, v5, s[36:37]
	s_nop 1
	v_mov_b32_dpp v74, v2 quad_perm:[2,3,0,1] row_mask:0xf bank_mask:0xf
	v_mov_b32_dpp v75, v3 quad_perm:[2,3,0,1] row_mask:0xf bank_mask:0xf
	v_mov_b32_dpp v72, v4 quad_perm:[2,3,0,1] row_mask:0xf bank_mask:0xf
	v_mov_b32_dpp v73, v5 quad_perm:[2,3,0,1] row_mask:0xf bank_mask:0xf
	v_cndmask_b32_e64 v2, v2, v72, s[50:51]
	v_cndmask_b32_e64 v3, v3, v73, s[50:51]
	v_cndmask_b32_e64 v4, v74, v4, s[50:51]
	v_cndmask_b32_e64 v5, v75, v5, s[50:51]
	s_waitcnt lgkmcnt(0)
	v_cvt_pk_bf16_f32 v30, v30, v31
	v_cvt_pk_bf16_f32 v31, v32, v33
	ds_write_b64 v209, v[30:31] offset:0
	v_cvt_pk_bf16_f32 v26, v26, v27
	v_cvt_pk_bf16_f32 v27, v28, v29
	ds_write_b64 v210, v[26:27] offset:0
	v_cvt_pk_bf16_f32 v22, v22, v23
	v_cvt_pk_bf16_f32 v23, v24, v25
	ds_write_b64 v211, v[22:23] offset:0
	v_cvt_pk_bf16_f32 v18, v18, v19
	v_cvt_pk_bf16_f32 v19, v20, v21
	ds_write_b64 v212, v[18:19] offset:0
	v_cvt_pk_bf16_f32 v14, v14, v15
	v_cvt_pk_bf16_f32 v15, v16, v17
	ds_write_b64 v209, v[14:15] offset:2048
	v_cvt_pk_bf16_f32 v10, v10, v11
	v_cvt_pk_bf16_f32 v11, v12, v13
	ds_write_b64 v210, v[10:11] offset:2048
	v_cvt_pk_bf16_f32 v6, v6, v7
	v_cvt_pk_bf16_f32 v7, v8, v9
	ds_write_b64 v211, v[6:7] offset:2048
	v_cvt_pk_bf16_f32 v2, v2, v3
	v_cvt_pk_bf16_f32 v3, v4, v5
	ds_write_b64 v212, v[2:3] offset:2048
	s_waitcnt lgkmcnt(0)
	ds_read_b128 v[76:79], v213 offset:0
	ds_read_b128 v[80:83], v213 offset:1024
	ds_read_b128 v[84:87], v213 offset:2048
	ds_read_b128 v[88:91], v213 offset:3072
	s_waitcnt lgkmcnt(3)
	v_add_u32_e32 v216, 0x40000, v214
	global_store_dwordx4 v216, v[76:79], s[16:17] sc1
	s_waitcnt lgkmcnt(2)
	v_add_u32_e32 v216, 0x50000, v214
	global_store_dwordx4 v216, v[80:83], s[16:17] sc1
	s_waitcnt lgkmcnt(1)
	v_add_u32_e32 v216, 0x60000, v214
	global_store_dwordx4 v216, v[84:87], s[16:17] sc1
	s_waitcnt lgkmcnt(0)
	v_add_u32_e32 v216, 0x70000, v214
	global_store_dwordx4 v216, v[88:91], s[16:17] sc1
	s_nop 1
	s_and_b64 vcc, exec, s[34:35]
	s_cbranch_vccnz .Lrelu2_nost2
	s_mov_b64 s[16:17], 0x100
	s_mov_b64 s[36:37], 0x4100
	s_mov_b64 s[38:39], 0x8100
	v_lshl_add_u64 v[70:71], v[66:67], 0, s[16:17]
	s_add_i32 m0, s8, 0x18000
	s_nop 0
	global_load_lds_dwordx4 v[70:71], off sc1
	v_lshl_add_u64 v[70:71], v[66:67], 0, s[36:37]
	s_mov_b32 m0, s45
	s_nop 0
	global_load_lds_dwordx4 v[70:71], off sc1
	v_lshl_add_u64 v[70:71], v[66:67], 0, s[38:39]
	s_mov_b32 m0, s46
	s_mov_b64 s[38:39], 0xc100
	global_load_lds_dwordx4 v[70:71], off sc1
	v_lshl_add_u64 v[66:67], v[66:67], 0, s[38:39]
	s_mov_b32 m0, s47
	s_nop 0
	global_load_lds_dwordx4 v[66:67], off sc1
	v_lshl_add_u64 v[66:67], v[68:69], 0, s[16:17]
	s_add_i32 m0, s9, 0x20000
	s_nop 0
	global_load_lds_dwordx4 v[66:67], off sc1
	v_lshl_add_u64 v[66:67], v[68:69], 0, s[36:37]
	s_mov_b32 m0, s48
	s_nop 0
	global_load_lds_dwordx4 v[66:67], off sc1

.Lrelu2_go:
	s_waitcnt lgkmcnt(0)
	s_barrier
	s_add_i32 s52, s49, s67
	s_cmpk_gt_i32 s52, 0x2ff
	s_cbranch_scc1 .Lm1_noasync
	s_mul_hi_i32 s53, s52, 0x2aaaaaab
	s_lshr_b32 s64, s53, 31
	s_ashr_i32 s53, s53, 2
	s_add_i32 s53, s53, s64
	s_mul_i32 s53, s53, 24
	s_sub_i32 s53, s52, s53
	s_lshl_b32 s53, s53, 7
	v_and_b32_e32 v227, 7, v137
	v_lshlrev_b32_e32 v227, 4, v227
	v_add_u32_e32 v227, s53, v227
	s_add_u32 s64, s94, 0xcbc8000
	s_addc_u32 s65, s95, 0
	global_load_dwordx4 v[232:235], v227, s[64:65] sc1
.Lm1_noasync:
	ds_read_b128 v[30:33], v133
	ds_read_b128 v[26:29], v134 offset:2048
	ds_read_b128 v[14:17], v134 offset:4096
	ds_read_b128 v[2:5], v134 offset:6144
	ds_read_b128 v[22:25], v135 offset:32768
	ds_read_b128 v[18:21], v161 offset:34816
	ds_read_b128 v[10:13], v161 offset:36864
	ds_read_b128 v[6:9], v161 offset:38912
	v_mov_b32_e32 v34, 0
	v_lshl_add_u64 v[116:117], v[112:113], 0, s[34:35]
	v_lshl_add_u64 v[118:119], v[114:115], 0, s[36:37]
	s_mov_b32 s6, -1
	s_mov_b32 s14, 0
	s_mov_b32 s19, 1
	s_mov_b32 s27, 0
	v_mov_b32_e32 v35, v34
	v_mov_b32_e32 v36, v34
	v_mov_b32_e32 v37, v34
	v_mov_b32_e32 v42, v34
	v_mov_b32_e32 v43, v34
	v_mov_b32_e32 v44, v34
	v_mov_b32_e32 v45, v34
	v_mov_b32_e32 v46, v34
	v_mov_b32_e32 v47, v34
	v_mov_b32_e32 v48, v34
	v_mov_b32_e32 v49, v34
	v_mov_b32_e32 v50, v34
	v_mov_b32_e32 v51, v34
	v_mov_b32_e32 v52, v34
	v_mov_b32_e32 v53, v34
	v_mov_b32_e32 v54, v34
	v_mov_b32_e32 v55, v34
	v_mov_b32_e32 v56, v34
	v_mov_b32_e32 v57, v34
	v_mov_b32_e32 v58, v34
	v_mov_b32_e32 v59, v34
	v_mov_b32_e32 v60, v34
	v_mov_b32_e32 v61, v34
	v_mov_b32_e32 v62, v34
	v_mov_b32_e32 v63, v34
	v_mov_b32_e32 v64, v34
	v_mov_b32_e32 v65, v34
	v_mov_b32_e32 v66, v34
	v_mov_b32_e32 v67, v34
	v_mov_b32_e32 v68, v34
	v_mov_b32_e32 v69, v34
	v_mov_b32_e32 v70, v34
	v_mov_b32_e32 v71, v34
	v_mov_b32_e32 v72, v34
	v_mov_b32_e32 v73, v34
	v_mov_b32_e32 v74, v34
	v_mov_b32_e32 v75, v34
	v_mov_b32_e32 v76, v34
	v_mov_b32_e32 v77, v34
	v_mov_b32_e32 v78, v34
	v_mov_b32_e32 v79, v34
	v_mov_b32_e32 v80, v34
	v_mov_b32_e32 v81, v34
	v_mov_b32_e32 v82, v34
	v_mov_b32_e32 v83, v34
	v_mov_b32_e32 v84, v34
	v_mov_b32_e32 v85, v34
	v_mov_b32_e32 v94, v34
	v_mov_b32_e32 v95, v34
	v_mov_b32_e32 v96, v34
	v_mov_b32_e32 v97, v34
	v_mov_b32_e32 v86, v34
	v_mov_b32_e32 v87, v34
	v_mov_b32_e32 v88, v34
	v_mov_b32_e32 v89, v34
	v_mov_b32_e32 v90, v34
	v_mov_b32_e32 v91, v34
	v_mov_b32_e32 v92, v34
	v_mov_b32_e32 v93, v34
	v_mov_b32_e32 v38, v34
	v_mov_b32_e32 v39, v34
	v_mov_b32_e32 v40, v34
	v_mov_b32_e32 v41, v34

.Lm1_nopend:
	v_mfma_f32_16x16x32_bf16 v[78:81], v[176:179], v[214:217], v[78:81]
	ds_read_b128 v[30:33], v2
	ds_read_b128 v[26:29], v2 offset:2048
	ds_read_b128 v[14:17], v2 offset:4096
	ds_read_b128 v[2:5], v2 offset:6144
	v_add_u32_e32 v7, v191, v181
	v_mfma_f32_16x16x32_bf16 v[74:77], v[176:179], v[218:221], v[74:77]
	s_mov_b32 m0, s34
	s_add_i32 s36, s36, s9
	s_add_i32 s27, s27, 1
	v_mfma_f32_16x16x32_bf16 v[70:73], v[176:179], v[222:225], v[70:73]
	v_lshl_add_u64 v[176:177], v[116:117], 0, v[100:101]
	v_lshl_add_u64 v[178:179], v[176:177], 0, s[84:85]
	v_mfma_f32_16x16x32_bf16 v[38:41], v[22:25], v[210:213], v[38:41]
	v_mfma_f32_16x16x32_bf16 v[90:93], v[22:25], v[214:217], v[90:93]
	v_mfma_f32_16x16x32_bf16 v[86:89], v[22:25], v[218:221], v[86:89]
	v_mfma_f32_16x16x32_bf16 v[94:97], v[22:25], v[222:225], v[94:97]
	ds_read_b128 v[22:25], v6
	ds_read_b128 v[18:21], v7
	v_add_u32_e32 v6, v191, v180
	ds_read_b128 v[10:13], v6
	ds_read_b128 v[6:9], v6 offset:2048
	global_load_lds_dwordx4 v[178:179], off sc1
	v_lshl_add_u64 v[178:179], v[176:177], 0, s[76:77]
	s_add_i32 m0, s34, 0x400
	v_mfma_f32_16x16x32_bf16 v[66:69], v[202:205], v[210:213], v[66:69]
	global_load_lds_dwordx4 v[178:179], off sc1
	v_lshl_add_u64 v[178:179], v[176:177], 0, s[54:55]
	s_add_i32 m0, s34, 0x800
	v_lshl_add_u64 v[176:177], v[176:177], 0, s[68:69]
	global_load_lds_dwordx4 v[178:179], off sc1
	s_add_i32 m0, s34, 0xc00
	s_mov_b64 s[34:35], 0x2300180
	global_load_lds_dwordx4 v[176:177], off sc1
	v_lshl_add_u64 v[176:177], v[118:119], 0, v[100:101]
	v_lshl_add_u64 v[178:179], v[176:177], 0, s[34:35]
	s_add_i32 m0, s36, 0x8000
	s_mov_b64 s[34:35], 0x2304180
	global_load_lds_dwordx4 v[178:179], off sc1
	v_lshl_add_u64 v[176:177], v[176:177], 0, s[34:35]
	s_add_i32 m0, s36, 0x8400
	v_mfma_f32_16x16x32_bf16 v[62:65], v[202:205], v[214:217], v[62:65]
	global_load_lds_dwordx4 v[176:177], off sc1
	v_mfma_f32_16x16x32_bf16 v[58:61], v[202:205], v[218:221], v[58:61]
	v_mfma_f32_16x16x32_bf16 v[54:57], v[202:205], v[222:225], v[54:57]
	v_mfma_f32_16x16x32_bf16 v[50:53], v[206:209], v[210:213], v[50:53]
	v_mfma_f32_16x16x32_bf16 v[46:49], v[206:209], v[214:217], v[46:49]
	v_mfma_f32_16x16x32_bf16 v[42:45], v[206:209], v[218:221], v[42:45]
	v_mfma_f32_16x16x32_bf16 v[34:37], v[206:209], v[222:225], v[34:37]
	s_add_i32 s6, s6, 1
	s_add_i32 s14, s14, 0xc000
	s_add_i32 s19, s19, 1
	v_lshl_add_u64 v[116:117], v[116:117], 0, s[2:3]
	s_cmp_eq_u32 s14, 0x9c000
	v_lshl_add_u64 v[118:119], v[118:119], 0, s[2:3]
	s_cbranch_scc0 .LBB0_84
	s_waitcnt lgkmcnt(0)
	v_mfma_f32_16x16x32_bf16 v[38:41], v[30:33], v[22:25], v[38:41]
	v_mfma_f32_16x16x32_bf16 v[90:93], v[30:33], v[18:21], v[90:93]
	v_mfma_f32_16x16x32_bf16 v[86:89], v[30:33], v[10:13], v[86:89]
	v_mfma_f32_16x16x32_bf16 v[30:33], v[30:33], v[6:9], v[94:97]
	v_mfma_f32_16x16x32_bf16 v[82:85], v[26:29], v[22:25], v[82:85]
	v_mfma_f32_16x16x32_bf16 v[78:81], v[26:29], v[18:21], v[78:81]
	v_mfma_f32_16x16x32_bf16 v[74:77], v[26:29], v[10:13], v[74:77]
	v_mfma_f32_16x16x32_bf16 v[26:29], v[26:29], v[6:9], v[70:73]
	v_mfma_f32_16x16x32_bf16 v[66:69], v[14:17], v[22:25], v[66:69]
	v_mfma_f32_16x16x32_bf16 v[62:65], v[14:17], v[18:21], v[62:65]
	v_mfma_f32_16x16x32_bf16 v[58:61], v[14:17], v[10:13], v[58:61]
	v_mfma_f32_16x16x32_bf16 v[14:17], v[14:17], v[6:9], v[54:57]
	v_mfma_f32_16x16x32_bf16 v[22:25], v[2:5], v[22:25], v[50:53]
	v_mfma_f32_16x16x32_bf16 v[18:21], v[2:5], v[18:21], v[46:49]
	s_nop 2
	ds_read_b128 v[46:49], v163
	ds_read_b128 v[50:53], v164 offset:2048
	ds_read_b128 v[54:57], v164 offset:4096
	ds_read_b128 v[70:73], v164 offset:6144
	v_mfma_f32_16x16x32_bf16 v[10:13], v[2:5], v[10:13], v[42:45]
	s_nop 2
	ds_read_b128 v[42:45], v165 offset:32768
	ds_read_b128 v[94:97], v166 offset:34816
	ds_read_b128 v[116:119], v166 offset:36864
	ds_read_b128 v[176:179], v166 offset:38912
	v_mfma_f32_16x16x32_bf16 v[2:5], v[2:5], v[6:9], v[34:37]
	s_waitcnt lgkmcnt(0)
	v_mfma_f32_16x16x32_bf16 v[6:9], v[46:49], v[42:45], v[38:41]
	s_waitcnt vmcnt(6)
	s_waitcnt lgkmcnt(0)
	s_barrier
	v_mfma_f32_16x16x32_bf16 v[34:37], v[46:49], v[94:97], v[90:93]
	v_mfma_f32_16x16x32_bf16 v[38:41], v[46:49], v[116:119], v[86:89]
	s_nop 1
	v_add_u32_e32 v90, 0x20800, v161
	v_mfma_f32_16x16x32_bf16 v[30:33], v[46:49], v[176:179], v[30:33]
	v_mfma_f32_16x16x32_bf16 v[46:49], v[50:53], v[42:45], v[82:85]
	v_mfma_f32_16x16x32_bf16 v[78:81], v[50:53], v[94:97], v[78:81]
	v_mfma_f32_16x16x32_bf16 v[74:77], v[50:53], v[116:119], v[74:77]
	v_mfma_f32_16x16x32_bf16 v[26:29], v[50:53], v[176:179], v[26:29]
	v_mfma_f32_16x16x32_bf16 v[50:53], v[54:57], v[42:45], v[66:69]
	v_mfma_f32_16x16x32_bf16 v[62:65], v[54:57], v[94:97], v[62:65]
	v_mfma_f32_16x16x32_bf16 v[58:61], v[54:57], v[116:119], v[58:61]
	v_mfma_f32_16x16x32_bf16 v[14:17], v[54:57], v[176:179], v[14:17]
	v_add_u32_e32 v54, v126, v120
	ds_read_b128 v[54:57], v54
	ds_read_b128 v[66:69], v167 offset:2048
	v_mfma_f32_16x16x32_bf16 v[18:21], v[70:73], v[94:97], v[18:21]
	v_add_u32_e32 v94, 0x21000, v161
	v_mfma_f32_16x16x32_bf16 v[10:13], v[70:73], v[116:119], v[10:13]
	v_add_u32_e32 v116, 0x21800, v161
	v_mfma_f32_16x16x32_bf16 v[22:25], v[70:73], v[42:45], v[22:25]
	ds_read_b128 v[42:45], v167 offset:4096
	ds_read_b128 v[82:85], v167 offset:6144
	ds_read_b128 v[86:89], v168
	ds_read_b128 v[90:93], v90
	ds_read_b128 v[94:97], v94
	ds_read_b128 v[116:119], v116
	v_mfma_f32_16x16x32_bf16 v[2:5], v[70:73], v[176:179], v[2:5]
	s_waitcnt lgkmcnt(0)
	v_mfma_f32_16x16x32_bf16 v[50:53], v[42:45], v[86:89], v[50:53]
	v_mfma_f32_16x16x32_bf16 v[62:65], v[42:45], v[90:93], v[62:65]
	v_mfma_f32_16x16x32_bf16 v[58:61], v[42:45], v[94:97], v[58:61]
	v_mfma_f32_16x16x32_bf16 v[14:17], v[42:45], v[116:119], v[14:17]
	v_add_u32_e32 v42, v126, v124
	v_mfma_f32_16x16x32_bf16 v[6:9], v[54:57], v[86:89], v[6:9]
	v_mfma_f32_16x16x32_bf16 v[34:37], v[54:57], v[90:93], v[34:37]
	v_mfma_f32_16x16x32_bf16 v[38:41], v[54:57], v[94:97], v[38:41]
	v_mfma_f32_16x16x32_bf16 v[30:33], v[54:57], v[116:119], v[30:33]
	v_mfma_f32_16x16x32_bf16 v[46:49], v[66:69], v[86:89], v[46:49]
	v_mfma_f32_16x16x32_bf16 v[54:57], v[66:69], v[90:93], v[78:81]
	v_mfma_f32_16x16x32_bf16 v[70:73], v[66:69], v[94:97], v[74:77]
	v_mfma_f32_16x16x32_bf16 v[26:29], v[66:69], v[116:119], v[26:29]
	ds_read_b128 v[42:45], v42
	ds_read_b128 v[66:69], v169
	ds_read_b128 v[74:77], v170
	ds_read_b128 v[78:81], v171
	v_mfma_f32_16x16x32_bf16 v[22:25], v[82:85], v[86:89], v[22:25]
	v_mfma_f32_16x16x32_bf16 v[18:21], v[82:85], v[90:93], v[18:21]
	v_mfma_f32_16x16x32_bf16 v[10:13], v[82:85], v[94:97], v[10:13]
	ds_read_b128 v[86:89], v172
	ds_read_b128 v[90:93], v173
	ds_read_b128 v[94:97], v174
	ds_read_b128 v[176:179], v175
	v_mfma_f32_16x16x32_bf16 v[2:5], v[82:85], v[116:119], v[2:5]
	s_waitcnt vmcnt(0)
	s_waitcnt lgkmcnt(0)
	v_mfma_f32_16x16x32_bf16 v[6:9], v[42:45], v[86:89], v[6:9]
	s_waitcnt lgkmcnt(0)
	s_barrier
	v_mfma_f32_16x16x32_bf16 v[34:37], v[42:45], v[90:93], v[34:37]
	v_mfma_f32_16x16x32_bf16 v[38:41], v[42:45], v[94:97], v[38:41]
	v_mfma_f32_16x16x32_bf16 v[30:33], v[42:45], v[176:179], v[30:33]
	v_mfma_f32_16x16x32_bf16 v[42:45], v[66:69], v[86:89], v[46:49]
	v_mfma_f32_16x16x32_bf16 v[46:49], v[66:69], v[90:93], v[54:57]
	v_mfma_f32_16x16x32_bf16 v[54:57], v[66:69], v[94:97], v[70:73]
	v_mfma_f32_16x16x32_bf16 v[26:29], v[66:69], v[176:179], v[26:29]
	v_mfma_f32_16x16x32_bf16 v[50:53], v[74:77], v[86:89], v[50:53]
	v_mfma_f32_16x16x32_bf16 v[62:65], v[74:77], v[90:93], v[62:65]
	v_mfma_f32_16x16x32_bf16 v[58:61], v[74:77], v[94:97], v[58:61]
	v_mfma_f32_16x16x32_bf16 v[14:17], v[74:77], v[176:179], v[14:17]
	ds_read_b128 v[66:69], v161 offset:38912
	ds_read_b128 v[70:73], v161 offset:36864
	ds_read_b128 v[74:77], v161 offset:34816
	ds_read_b128 v[82:85], v135 offset:32768
	v_mfma_f32_16x16x32_bf16 v[22:25], v[78:81], v[86:89], v[22:25]
	v_mfma_f32_16x16x32_bf16 v[18:21], v[78:81], v[90:93], v[18:21]
	v_mfma_f32_16x16x32_bf16 v[10:13], v[78:81], v[94:97], v[10:13]
	ds_read_b128 v[86:89], v134 offset:6144
	ds_read_b128 v[90:93], v134 offset:4096
	ds_read_b128 v[94:97], v134 offset:2048
	ds_read_b128 v[116:119], v133
	v_mfma_f32_16x16x32_bf16 v[2:5], v[78:81], v[176:179], v[2:5]
	s_waitcnt lgkmcnt(0)
	v_mfma_f32_16x16x32_bf16 v[78:81], v[94:97], v[74:77], v[46:49]
	s_nop 2
	v_add_u32_e32 v46, v105, v124
	v_mfma_f32_16x16x32_bf16 v[6:9], v[116:119], v[82:85], v[6:9]
	v_add_u32_e32 v47, v121, v124
	v_mfma_f32_16x16x32_bf16 v[34:37], v[116:119], v[74:77], v[34:37]
	v_mfma_f32_16x16x32_bf16 v[38:41], v[116:119], v[70:73], v[38:41]
	v_mfma_f32_16x16x32_bf16 v[30:33], v[116:119], v[66:69], v[30:33]
	v_mfma_f32_16x16x32_bf16 v[42:45], v[94:97], v[82:85], v[42:45]
	v_mfma_f32_16x16x32_bf16 v[116:119], v[94:97], v[70:73], v[54:57]
	v_mfma_f32_16x16x32_bf16 v[26:29], v[94:97], v[66:69], v[26:29]
	v_mfma_f32_16x16x32_bf16 v[94:97], v[90:93], v[82:85], v[50:53]
	v_mfma_f32_16x16x32_bf16 v[176:179], v[90:93], v[74:77], v[62:65]
	v_mfma_f32_16x16x32_bf16 v[202:205], v[90:93], v[70:73], v[58:61]
	v_mfma_f32_16x16x32_bf16 v[14:17], v[90:93], v[66:69], v[14:17]
	v_mfma_f32_16x16x32_bf16 v[82:85], v[86:89], v[82:85], v[22:25]
	s_nop 2
	ds_read_b128 v[22:25], v46
	ds_read_b128 v[90:93], v47 offset:2048
	v_add_u32_e32 v46, v122, v124
	v_mfma_f32_16x16x32_bf16 v[74:77], v[86:89], v[74:77], v[18:21]
	s_nop 2
	ds_read_b128 v[18:21], v47 offset:4096
	ds_read_b128 v[206:209], v47 offset:6144
	v_add_u32_e32 v47, v123, v124
	v_mfma_f32_16x16x32_bf16 v[70:73], v[86:89], v[70:73], v[10:13]
	s_nop 2
	ds_read_b128 v[10:13], v46 offset:32768
	ds_read_b128 v[210:213], v47 offset:34816
	ds_read_b128 v[214:217], v47 offset:36864
	ds_read_b128 v[218:221], v47 offset:38912
	v_mfma_f32_16x16x32_bf16 v[2:5], v[86:89], v[66:69], v[2:5]
	s_waitcnt lgkmcnt(0)
	v_mfma_f32_16x16x32_bf16 v[62:65], v[22:25], v[10:13], v[6:9]
	s_waitcnt vmcnt(0)
	s_waitcnt lgkmcnt(0)
	s_barrier
	v_mfma_f32_16x16x32_bf16 v[58:61], v[22:25], v[210:213], v[34:37]
	v_mfma_f32_16x16x32_bf16 v[54:57], v[22:25], v[214:217], v[38:41]
	v_mfma_f32_16x16x32_bf16 v[50:53], v[22:25], v[218:221], v[30:33]
	v_mfma_f32_16x16x32_bf16 v[46:49], v[90:93], v[10:13], v[42:45]
	v_mfma_f32_16x16x32_bf16 v[42:45], v[90:93], v[210:213], v[78:81]
	v_mfma_f32_16x16x32_bf16 v[38:41], v[90:93], v[214:217], v[116:119]
	v_mfma_f32_16x16x32_bf16 v[34:37], v[90:93], v[218:221], v[26:29]
	v_mfma_f32_16x16x32_bf16 v[30:33], v[18:21], v[10:13], v[94:97]
	v_mfma_f32_16x16x32_bf16 v[26:29], v[18:21], v[210:213], v[176:179]
	v_mfma_f32_16x16x32_bf16 v[22:25], v[18:21], v[214:217], v[202:205]
	v_mfma_f32_16x16x32_bf16 v[18:21], v[18:21], v[218:221], v[14:17]
	v_mfma_f32_16x16x32_bf16 v[14:17], v[206:209], v[10:13], v[82:85]
	v_mfma_f32_16x16x32_bf16 v[10:13], v[206:209], v[210:213], v[74:77]
	v_mfma_f32_16x16x32_bf16 v[6:9], v[206:209], v[214:217], v[70:73]
	v_mfma_f32_16x16x32_bf16 v[2:5], v[206:209], v[218:221], v[2:5]
	s_waitcnt lgkmcnt(0)
	s_barrier
	s_load_dword s6, s[78:79], 0x0
	s_waitcnt lgkmcnt(0)
	s_add_i32 s49, s6, s49
	s_cmpk_gt_i32 s49, 0x2ff
	s_cselect_b64 s[34:35], -1, 0
	s_cmpk_lt_i32 s49, 0x300
	s_cbranch_scc0 .LBB0_80
	s_mul_hi_i32 s6, s49, 0x2aaaaaab
	s_lshr_b32 s14, s6, 31
	s_ashr_i32 s6, s6, 2
	s_add_i32 s6, s6, s14
	s_mul_i32 s14, s6, 24
	s_sub_i32 s14, s49, s14
	v_readlane_b32 s52, v255, 40
	s_add_i32 s52, s52, 0x5d0e1000
	v_cmp_ne_u32_e32 vcc, s52, v232
	s_cbranch_vccz .Lm1ok_b
	s_lshl_b32 s53, s14, 7
	s_add_u32 s64, s94, 0xcbc8000
	s_addc_u32 s65, s95, 0
	v_and_b32_e32 v226, 7, v137
	v_lshlrev_b32_e32 v226, 4, v226
	v_add_u32_e32 v226, s53, v226
	s_mov_b32 s53, 0x100000
